# v34 + every wave touches its first P1 row of x / first two P5 rows of o|z and XC between the join and the closing s_barrier of grid barriers 1 and 5 (loads fly during the barrier protocol)
# baseline (speedup 1.0000x reference)
.LBB0_208:
	s_or_b64 exec, exec, s[0:1]
	v_readfirstlane_b32 s3, v184
	s_lshr_b32 s3, s3, 6
	s_lshl_b32 s3, s3, 2
	s_lshl_b32 s4, s2, 5
	s_add_u32 s3, s3, s4
	v_readlane_b32 s4, v254, 10
	v_readlane_b32 s5, v254, 11
	v_readlane_b32 s8, v254, 12
	v_readlane_b32 s9, v254, 13
	s_cmp_lt_u32 s3, 0x1000
	s_cselect_b64 s[4:5], s[4:5], s[8:9]
	s_and_b32 s3, s3, 0xfff
	s_lshl_b32 s3, s3, 13
	s_add_u32 s4, s4, s3
	s_addc_u32 s5, s5, 0
	v_mbcnt_lo_u32_b32 v0, -1, 0
	v_mbcnt_hi_u32_b32 v0, -1, v0
	v_lshlrev_b32_e32 v0, 7, v0
	global_load_dword v255, v0, s[4:5]
	v_mov_b32_e32 v108, v184
	s_waitcnt lgkmcnt(0)
	s_barrier
	s_cmp_gt_i32 s2, 2
	v_readfirstlane_b32 s3, v108
	s_cbranch_scc1 .LBB0_214
	s_waitcnt vmcnt(13)
	v_add_u32_e32 v8, 0x1000, v108
	v_ashrrev_i32_e32 v109, 31, v108
	v_readlane_b32 s36, v254, 26
	v_readlane_b32 s20, v254, 0
	v_ashrrev_i32_e32 v9, 31, v8
	s_movk_i32 s0, 0x800
	v_lshlrev_b64 v[6:7], 2, v[108:109]
	v_readlane_b32 s38, v254, 28
	v_readlane_b32 s39, v254, 29
	v_readlane_b32 s50, v254, 40
	v_readlane_b32 s51, v254, 41
	v_readlane_b32 s21, v254, 1
	v_readlane_b32 s22, v254, 2
	v_readlane_b32 s23, v254, 3
	v_lshl_add_u64 v[8:9], v[8:9], 2, s[28:29]
	s_mov_b64 s[14:15], 0x100000
	v_cmp_gt_i32_e64 s[0:1], s0, v108
	s_waitcnt vmcnt(11)
	v_add_u32_e32 v16, 0xfffffe00, v108
	v_lshl_add_u64 v[0:1], s[70:71], 0, v[6:7]
	v_lshl_add_u64 v[2:3], s[28:29], 0, v[6:7]
	s_mul_i32 s4, s2, 0x1800
	s_mul_i32 s16, s30, 0x1800
	s_mov_b64 s[38:39], s[80:81]
	v_lshl_add_u64 v[4:5], s[50:51], 0, v[6:7]
	s_mul_i32 s8, s2, 0x3000
	s_mul_i32 s17, s30, 0x3000
	v_lshl_add_u64 v[6:7], s[20:21], 0, v[6:7]
	v_lshl_add_u64 v[8:9], v[8:9], 0, s[14:15]
	s_movk_i32 s22, 0x5ff
	s_mov_b32 s23, s2
	v_readlane_b32 s37, v254, 27
	v_readlane_b32 s40, v254, 30
	v_readlane_b32 s41, v254, 31
	v_readlane_b32 s42, v254, 32
	v_readlane_b32 s43, v254, 33
	v_readlane_b32 s44, v254, 34
	v_readlane_b32 s45, v254, 35
	v_readlane_b32 s46, v254, 36
	v_readlane_b32 s47, v254, 37
	v_readlane_b32 s48, v254, 38
	v_readlane_b32 s49, v254, 39
	v_readlane_b32 s24, v254, 4
	v_readlane_b32 s25, v254, 5
	v_readlane_b32 s26, v254, 6
	v_readlane_b32 s27, v254, 7
	s_branch .LBB0_211

.LBB0_802:
	s_or_b64 exec, exec, s[0:1]
	s_waitcnt vmcnt(9)
	v_readfirstlane_b32 s3, v184
	s_lshr_b32 s3, s3, 6
	s_add_u32 s3, s3, s76
	s_mul_i32 s6, s3, 0x3000
	s_add_u32 s4, s28, 0x8501000
	s_addc_u32 s5, s29, 0
	s_add_u32 s4, s4, s6
	s_addc_u32 s5, s5, 0
	s_lshl_b32 s6, s3, 12
	s_add_u32 s8, s28, 0xe500000
	s_addc_u32 s9, s29, 0
	s_add_u32 s8, s8, s6
	s_addc_u32 s9, s9, 0
	v_mbcnt_hi_u32_b32 v0, -1, v185
	v_lshlrev_b32_e32 v0, 6, v0
	global_load_dword v255, v0, s[4:5]
	global_load_dword v255, v0, s[8:9]
	s_add_u32 s4, s4, 0x1800000
	s_addc_u32 s5, s5, 0
	s_add_u32 s8, s8, 0x800000
	s_addc_u32 s9, s9, 0
	global_load_dword v255, v0, s[4:5]
	global_load_dword v255, v0, s[8:9]
	s_nop 0
	v_mov_b32_e32 v24, v184
	s_waitcnt lgkmcnt(0)
	s_barrier
	s_nop 0
	v_readfirstlane_b32 s0, v24
	s_ashr_i32 s0, s0, 6
	s_add_i32 s14, s0, s76
	s_cmpk_gt_i32 s14, 0x1fff
	s_cbranch_scc1 .LBB0_809
	v_readlane_b32 s80, v254, 26
	s_waitcnt vmcnt(7)
	v_and_b32_e32 v34, 63, v24
	v_readlane_b32 s88, v254, 34
	v_readlane_b32 s89, v254, 35
	v_lshlrev_b32_e32 v32, 6, v34
	v_readlane_b32 s90, v254, 36
	v_readlane_b32 s91, v254, 37
	s_mov_b64 s[8:9], s[88:89]
	s_mov_b64 s[10:11], s[90:91]
	global_load_dwordx4 v[0:3], v32, s[8:9]
	global_load_dwordx4 v[4:7], v32, s[10:11]
	global_load_dwordx4 v[8:11], v32, s[8:9] offset:16
	global_load_dwordx4 v[12:15], v32, s[10:11] offset:16
	global_load_dwordx4 v[16:19], v32, s[8:9] offset:32
	global_load_dwordx4 v[20:23], v32, s[10:11] offset:32
	v_readlane_b32 s86, v254, 32
	v_readlane_b32 s87, v254, 33
	v_and_b32_e32 v33, 60, v24
	s_nop 3
	global_load_dword v144, v33, s[86:87]
	global_load_dwordx4 v[24:27], v32, s[8:9] offset:48
	global_load_dwordx4 v[28:31], v32, s[10:11] offset:48
	v_mov_b32_e32 v33, 0
	s_waitcnt vmcnt(12)
	v_mbcnt_hi_u32_b32 v38, -1, v185
	v_lshlrev_b32_e32 v32, 4, v34
	v_lshlrev_b32_e32 v34, 5, v34
	v_mov_b32_e32 v35, v33
	s_waitcnt vmcnt(11)
	v_and_b32_e32 v40, 64, v38
	v_xor_b32_e32 v39, 1, v38
	v_lshl_add_u64 v[36:37], s[28:29], 0, v[34:35]
	v_lshl_add_u64 v[146:147], s[50:51], 0, v[34:35]
	v_add_u32_e32 v34, 64, v40
	v_xor_b32_e32 v41, 2, v38
	v_cmp_lt_i32_e32 vcc, v39, v34
	v_xor_b32_e32 v42, 4, v38
	v_lshl_add_u64 v[148:149], s[62:63], 0, v[32:33]
	v_cndmask_b32_e32 v32, v38, v39, vcc
	v_cmp_lt_i32_e32 vcc, v41, v34
	v_xor_b32_e32 v43, 8, v38
	s_mov_b64 s[20:21], 0x10500000
	v_cndmask_b32_e32 v33, v38, v41, vcc
	v_cmp_lt_i32_e32 vcc, v42, v34
	s_mov_b64 s[22:23], 0xe500000
	s_waitcnt vmcnt(10)
	v_xor_b32_e32 v44, 16, v38
	v_cndmask_b32_e32 v35, v38, v42, vcc
	v_cmp_lt_i32_e32 vcc, v43, v34
	v_xor_b32_e32 v45, 32, v38
	v_lshl_add_u64 v[150:151], v[36:37], 0, s[20:21]
	v_lshl_add_u64 v[152:153], v[36:37], 0, s[22:23]
	v_cndmask_b32_e32 v36, v38, v43, vcc
	v_cmp_lt_i32_e32 vcc, v44, v34
	s_mov_b64 s[6:7], s[86:87]
	s_mov_b32 s12, 0x3a800000
	v_cndmask_b32_e32 v37, v38, v44, vcc
	v_cmp_lt_i32_e32 vcc, v45, v34
	s_mov_b64 s[0:1], 0x1000000
	s_mov_b32 s3, 0x1000000
	v_cndmask_b32_e32 v34, v38, v45, vcc
	s_mov_b64 s[4:5], 0x2000000
	s_brev_b32 s16, 64
	s_mov_b64 s[6:7], 0x3000000
	s_mov_b32 s17, 0x3000000
	s_mov_b64 s[8:9], 0x1000
	s_movk_i32 s18, 0x1000
	s_mov_b64 s[10:11], 0x1800
	s_mov_b32 s13, 0x3b800000
	s_mov_b32 s19, 0x800000
	v_mov_b32_e32 v155, 0x3000
	v_lshlrev_b32_e32 v170, 2, v32
	v_lshlrev_b32_e32 v171, 2, v33
	v_lshlrev_b32_e32 v172, 2, v35
	v_lshlrev_b32_e32 v173, 2, v36
	v_lshlrev_b32_e32 v174, 2, v37
	v_lshlrev_b32_e32 v175, 2, v34
	v_mov_b32_e32 v154, 0x358637bd
	v_readlane_b32 s81, v254, 27
	v_readlane_b32 s82, v254, 28
	v_readlane_b32 s83, v254, 29
	v_readlane_b32 s84, v254, 30
	v_readlane_b32 s85, v254, 31
	v_readlane_b32 s92, v254, 38
	v_readlane_b32 s93, v254, 39
	v_readlane_b32 s94, v254, 40
	v_readlane_b32 s95, v254, 41
	s_waitcnt vmcnt(2)
	v_mov_b32_e32 v145, v144
	s_branch .LBB0_805
